# v40_nsak
# baseline (speedup 1.0000x reference)
; #define BODY_S(KF, vA, KEY0) { f32x16 x = qk64(KF, qf); const bool fs_ = allmem && ((KEY0) + 31 <= t0); \
;             TOK_Y(x, KEY0, fs_, (member && dist >= 0)) \
;             osm_u(x, -slope2 * (float)(t0 - (KEY0)), m, l, o); pv64(vA, x, o); }
; DI void nsa_item8(const Ctx& c, int q8, int g, LAS unsigned char* lds, int wave, int lane_in, float kbound) {
;     ...
;         int cur, nb; PREVBLK(0x7fffffff, cur, nb)
;     ...
;         while (nb >= 0) {
;             const bool member = cur == nb; const bool allmem = !__any(!member);
;             const int key0 = nb * 64;
;             bf16x8 k0[4], k1[4]; bf16x8 w0[4], w1[4];
;             ldk64(k0, Ksp + (size_t)(key0 + 32) * PP); ldk64(k1, Ksp + (size_t)key0 * PP); ldv64(w0, Vsp + (size_t)(nb * 2 + 1) * 32768, 32); ldv64(w1, Vsp + (size_t)(nb * 2) * 32768, 32);
;             int ncur, nn; PREVBLK(nb, ncur, nn)
;             if (key0 + 32 <= t0 + 7) BODY_S(k0, w0, key0 + 32)
;             BODY_S(k1, w1, key0)
.LBB0_597:
	v_lshlrev_b32_e32 v190, 6, v50
	v_mad_u64_u32 v[34:35], s[6:7], v190, s56, v[158:159]
	v_lshlrev_b32_e32 v0, 1, v50
	global_load_dwordx4 v[110:113], v[34:35], off
	global_load_dwordx4 v[106:109], v[34:35], off offset:32
	global_load_dwordx4 v[98:101], v[34:35], off offset:64
	global_load_dwordx4 v[102:105], v[34:35], off offset:96
	v_lshlrev_b64 v[34:35], 16, v[0:1]
	v_lshl_add_u64 v[34:35], v[160:161], 0, v[34:35]
	global_load_dwordx4 v[94:97], v[34:35], off
	global_load_dwordx4 v[90:93], v[34:35], off offset:16
	global_load_dwordx4 v[82:85], v[34:35], off offset:2048
	global_load_dwordx4 v[86:89], v[34:35], off offset:2064
	v_or_b32_e32 v223, 32, v190
	v_mad_u64_u32 v[228:229], s[6:7], v223, s56, v[158:159]
	global_load_dwordx4 v[34:37], v[228:229], off
	global_load_dwordx4 v[38:41], v[228:229], off offset:32
	global_load_dwordx4 v[240:243], v[228:229], off offset:64
	global_load_dwordx4 v[248:251], v[228:229], off offset:96
	v_cmp_eq_u32_e64 s[8:9], 0, v50
	v_cmp_eq_u32_e64 s[6:7], v180, v50
	v_cmp_ne_u32_e32 vcc, v180, v50
	v_cndmask_b32_e64 v224, 0, -1, s[8:9]
	v_max_i32_e32 v225, s24, v224
	v_cmp_lt_i32_e64 s[8:9], s24, v50
	s_cmp_eq_u64 vcc, 0
	v_or_b32_e32 v191, 32, v190
	v_cndmask_b32_e64 v225, v224, v225, s[8:9]
	v_max_i32_e32 v225, s34, v225
	v_cmp_gt_i32_e64 s[8:9], s24, v50
	v_cmp_ge_i32_e32 vcc, s25, v191
	s_nop 0
	v_cndmask_b32_e64 v224, v225, v224, s[8:9]
	v_max_i32_e32 v225, v171, v224
	v_cmp_lt_i32_e64 s[8:9], v171, v50
	s_nop 1
	v_cndmask_b32_e64 v224, v224, v225, s[8:9]
	v_max_i32_e32 v225, v184, v224
	v_cmp_lt_i32_e64 s[8:9], v184, v50
	s_nop 1
	v_cndmask_b32_e64 v224, v224, v225, s[8:9]
	v_max_i32_e32 v225, v186, v224
	v_cmp_lt_i32_e64 s[8:9], v186, v50
	s_nop 1
	v_cndmask_b32_e64 v224, v224, v225, s[8:9]
	v_max_i32_e32 v225, v187, v224
	v_cmp_lt_i32_e64 s[8:9], v187, v50
	s_nop 1
	v_cndmask_b32_e64 v224, v224, v225, s[8:9]
	v_max_i32_e32 v225, v185, v224
	v_cmp_lt_i32_e64 s[8:9], v185, v50
	s_nop 1
	v_cndmask_b32_e64 v180, v224, v225, s[8:9]
	ds_bpermute_b32 v224, v157, v180
	s_cselect_b64 s[8:9], -1, 0
	s_waitcnt lgkmcnt(0)
	v_max_i32_e32 v224, v224, v180
	ds_bpermute_b32 v225, v176, v224
	s_waitcnt lgkmcnt(0)
	v_max_i32_e32 v224, v225, v224
	ds_bpermute_b32 v225, v177, v224
	s_waitcnt lgkmcnt(0)
	v_max_i32_e32 v224, v225, v224
	ds_bpermute_b32 v225, v178, v224
	s_waitcnt lgkmcnt(0)
	v_max_i32_e32 v224, v225, v224
	ds_bpermute_b32 v225, v179, v224
	s_waitcnt lgkmcnt(0)
	v_max_i32_e32 v188, v225, v224
	ds_bpermute_b32 v189, v181, v188
	s_and_saveexec_b64 s[12:13], vcc
	s_cbranch_execz .Lnsa_skip1
	v_or_b32_e32 v0, 1, v0
	s_xor_b64 s[50:51], s[8:9], -1
	v_lshlrev_b64 v[42:43], 16, v[0:1]
	v_lshl_add_u64 v[42:43], v[160:161], 0, v[42:43]
	global_load_dwordx4 v[126:129], v[42:43], off
	global_load_dwordx4 v[122:125], v[42:43], off offset:16
	global_load_dwordx4 v[118:121], v[42:43], off offset:2048
	global_load_dwordx4 v[114:117], v[42:43], off offset:2064
	v_or_b32_e32 v0, 63, v190
	v_cmp_lt_u32_e32 vcc, s49, v0
	s_or_b64 s[50:51], s[50:51], vcc
	s_waitcnt vmcnt(7)
	v_mfma_f32_32x32x16_bf16 v[50:65], v[34:37], v[66:69], 0
	s_waitcnt vmcnt(6)
	v_mfma_f32_32x32x16_bf16 v[50:65], v[38:41], v[70:73], v[50:65]
	s_waitcnt vmcnt(5)
	v_mfma_f32_32x32x16_bf16 v[50:65], v[240:243], v[74:77], v[50:65]
	s_waitcnt vmcnt(4)
	v_mfma_f32_32x32x16_bf16 v[50:65], v[248:251], v[78:81], v[50:65]
	s_and_saveexec_b64 s[52:53], s[50:51]
	s_xor_b64 s[50:51], exec, s[52:53]
	s_cbranch_execz .LBB0_600
	v_add_u32_e32 v0, v191, v201
	v_cmp_ge_i32_e32 vcc, v134, v0
	s_nop 6
	v_fmamk_f32 v34, v50, 0x3e38aa3b, v138
	s_and_b64 vcc, s[6:7], vcc
	v_cndmask_b32_e32 v34, v237, v34, vcc
	v_cmp_gt_i32_e32 vcc, v134, v0
	v_fmamk_f32 v35, v51, 0x3e38aa3b, v139
	s_and_b64 vcc, s[6:7], vcc
	v_or_b32_e32 v36, 2, v0
	v_cndmask_b32_e32 v35, v237, v35, vcc
	v_cmp_ge_i32_e32 vcc, v134, v36
	v_fmamk_f32 v36, v52, 0x3e38aa3b, v140
	s_and_b64 vcc, s[6:7], vcc
	v_or_b32_e32 v37, 3, v0
	v_cndmask_b32_e32 v36, v237, v36, vcc
	v_cmp_ge_i32_e32 vcc, v134, v37
	v_fmamk_f32 v37, v53, 0x3e38aa3b, v141
	s_and_b64 vcc, s[6:7], vcc
	v_add_u32_e32 v38, 8, v0
	v_cndmask_b32_e32 v37, v237, v37, vcc
	v_cmp_ge_i32_e32 vcc, v134, v38
	v_fmamk_f32 v38, v54, 0x3e38aa3b, v142
	s_and_b64 vcc, s[6:7], vcc
	v_add_u32_e32 v39, 9, v0
	v_cndmask_b32_e32 v38, v237, v38, vcc
	v_cmp_ge_i32_e32 vcc, v134, v39
	v_fmamk_f32 v39, v55, 0x3e38aa3b, v143
	s_and_b64 vcc, s[6:7], vcc
	v_add_u32_e32 v40, 10, v0
	v_cndmask_b32_e32 v39, v237, v39, vcc
	v_cmp_ge_i32_e32 vcc, v134, v40
	v_fmamk_f32 v40, v56, 0x3e38aa3b, v144
	s_and_b64 vcc, s[6:7], vcc
	v_add_u32_e32 v41, 11, v0
	v_cndmask_b32_e32 v40, v237, v40, vcc
	v_cmp_ge_i32_e32 vcc, v134, v41
	v_fmamk_f32 v41, v57, 0x3e38aa3b, v145
	s_and_b64 vcc, s[6:7], vcc
	v_add_u32_e32 v42, 16, v0
	v_cndmask_b32_e32 v41, v237, v41, vcc
	v_cmp_ge_i32_e32 vcc, v134, v42
	v_fmamk_f32 v42, v58, 0x3e38aa3b, v146
	s_and_b64 vcc, s[6:7], vcc
	v_add_u32_e32 v43, 17, v0
	v_cndmask_b32_e32 v42, v237, v42, vcc
	v_cmp_ge_i32_e32 vcc, v134, v43
	v_fmamk_f32 v43, v59, 0x3e38aa3b, v147
	s_and_b64 vcc, s[6:7], vcc
	v_add_u32_e32 v44, 18, v0
	v_cndmask_b32_e32 v43, v237, v43, vcc
	v_cmp_ge_i32_e32 vcc, v134, v44
	v_fmamk_f32 v44, v60, 0x3e38aa3b, v148
	s_and_b64 vcc, s[6:7], vcc
	v_add_u32_e32 v45, 19, v0
	v_cndmask_b32_e32 v44, v237, v44, vcc
	v_cmp_ge_i32_e32 vcc, v134, v45
	v_fmamk_f32 v45, v61, 0x3e38aa3b, v149
	s_and_b64 vcc, s[6:7], vcc
	v_add_u32_e32 v46, 24, v0
	v_cndmask_b32_e32 v45, v237, v45, vcc
	v_cmp_ge_i32_e32 vcc, v134, v46
	v_fmamk_f32 v46, v62, 0x3e38aa3b, v150
	s_and_b64 vcc, s[6:7], vcc
	v_add_u32_e32 v47, 25, v0
	v_cndmask_b32_e32 v46, v237, v46, vcc
	v_cmp_ge_i32_e32 vcc, v134, v47
	v_fmamk_f32 v47, v63, 0x3e38aa3b, v151
	s_and_b64 vcc, s[6:7], vcc
	v_add_u32_e32 v48, 26, v0
	v_cndmask_b32_e32 v47, v237, v47, vcc
	v_cmp_ge_i32_e32 vcc, v134, v48
	v_fmamk_f32 v48, v64, 0x3e38aa3b, v152
	s_and_b64 vcc, s[6:7], vcc
	v_add_u32_e32 v0, 27, v0
	v_cndmask_b32_e32 v48, v237, v48, vcc
	v_cmp_ge_i32_e32 vcc, v134, v0
	v_fmamk_f32 v0, v65, 0x3e38aa3b, v153
	s_and_b64 vcc, s[6:7], vcc
	v_cndmask_b32_e32 v49, v237, v0, vcc

; DI float ex2(float x) { return __builtin_amdgcn_exp2f(x); }
; DI void both_halves(float x, float& lo, float& hi) { auto rr = __builtin_amdgcn_permlane32_swap(__float_as_uint(x), __float_as_uint(x), false, false); lo = __uint_as_float(rr[0]); hi = __uint_as_float(rr[1]); }
; #define BODY_S(KF, vA, KEY0) { f32x16 x = qk64(KF, qf); const bool fs_ = allmem && ((KEY0) + 31 <= t0); \
;             TOK_Y(x, KEY0, fs_, (member && dist >= 0)) \
;             osm_u(x, -slope2 * (float)(t0 - (KEY0)), m, l, o); pv64(vA, x, o); }
; DI void osm_u(f32x16& x, float u, float& m, float& l, f32x16 (&o)[2]) {
;     float tm = x[0];
; #pragma unroll
;     for (int i = 1; i < 16; ++i) tm = fmaxf(tm, x[i]);
;     float lo, hi; both_halves(tm, lo, hi); tm = fmaxf(lo, hi);
;     const float mn = fmaxf(m, tm + u);
;     if (__any(mn != m)) { const float alpha = ex2(m - mn); l *= alpha; o[0] = o[0] * alpha; o[1] = o[1] * alpha; m = mn; }
;     const float sh = u - m; float ps = 0.f;
; #pragma unroll
;     for (int i = 0; i < 16; ++i) { x[i] = ex2(x[i] + sh); ps += x[i]; }
;     l += ps;
; }
; DI void nsa_item8(const Ctx& c, int q8, int g, LAS unsigned char* lds, int wave, int lane_in, float kbound) {
;     ...
;             BODY_S(k1, w1, key0)
.LBB0_606:
	v_mul_f32_e64 v0, -v132, v0
	v_sub_f32_e32 v0, v0, v50
	v_add_f32_e32 v34, v34, v0
	v_exp_f32_e32 v34, v34
	v_add_f32_e32 v35, v35, v0
	v_exp_f32_e32 v35, v35
	v_add_f32_e32 v36, v36, v0
	v_exp_f32_e32 v36, v36
	v_add_f32_e32 v37, v37, v0
	v_add_f32_e32 v38, v38, v0
	v_add_f32_e32 v39, v39, v0
	v_add_f32_e32 v40, v40, v0
	v_add_f32_e32 v41, v41, v0
	v_exp_f32_e32 v37, v37
	v_exp_f32_e32 v38, v38
	v_exp_f32_e32 v39, v39
	v_exp_f32_e32 v40, v40
	v_exp_f32_e32 v41, v41
	v_add_f32_e32 v50, 0, v34
	v_add_f32_e32 v50, v35, v50
	v_add_f32_e32 v50, v36, v50
	v_add_f32_e32 v50, v37, v50
	v_cvt_pk_bf16_f32 v34, v34, v35
	v_cvt_pk_bf16_f32 v35, v36, v37
	v_cvt_pk_bf16_f32 v36, v38, v39
	v_cvt_pk_bf16_f32 v37, v40, v41
	v_add_f32_e32 v42, v42, v0
	v_add_f32_e32 v43, v43, v0
	s_waitcnt vmcnt(3)
	v_mfma_f32_32x32x16_bf16 v[18:33], v[126:129], v[34:37], v[18:33]
	v_add_f32_e32 v44, v44, v0
	v_add_f32_e32 v45, v45, v0
	v_add_f32_e32 v46, v46, v0
	v_add_f32_e32 v47, v47, v0
	v_add_f32_e32 v48, v48, v0
	v_add_f32_e32 v0, v49, v0
	v_add_f32_e32 v50, v38, v50
	s_waitcnt vmcnt(1)
	v_mfma_f32_32x32x16_bf16 v[2:17], v[118:121], v[34:37], v[2:17]
	v_exp_f32_e32 v42, v42
	v_exp_f32_e32 v43, v43
	v_exp_f32_e32 v44, v44
	v_exp_f32_e32 v45, v45
	v_exp_f32_e32 v46, v46
	v_exp_f32_e32 v47, v47
	v_exp_f32_e32 v48, v48
	v_exp_f32_e32 v0, v0
	v_add_f32_e32 v50, v39, v50
	v_add_f32_e32 v50, v40, v50
	v_add_f32_e32 v50, v41, v50
	v_add_f32_e32 v50, v42, v50
	v_cvt_pk_bf16_f32 v38, v42, v43
	v_cvt_pk_bf16_f32 v39, v44, v45
	v_cvt_pk_bf16_f32 v40, v46, v47
	v_cvt_pk_bf16_f32 v41, v48, v0
	v_add_f32_e32 v50, v43, v50
	v_add_f32_e32 v50, v44, v50
	v_mfma_f32_32x32x16_bf16 v[18:33], v[122:125], v[38:41], v[18:33]
	v_add_f32_e32 v50, v45, v50
	v_add_f32_e32 v50, v46, v50
	v_add_f32_e32 v50, v47, v50
	v_add_f32_e32 v50, v48, v50
	v_add_f32_e32 v49, v0, v50
	v_add_f32_e32 v182, v182, v49
	s_waitcnt vmcnt(0)
	v_mfma_f32_32x32x16_bf16 v[2:17], v[114:117], v[38:41], v[2:17]
.Lnsa_skip1:
	s_waitcnt vmcnt(0)
.LBB0_607:
	s_or_b64 exec, exec, s[12:13]
	s_waitcnt vmcnt(7)
	v_mfma_f32_32x32x16_bf16 v[50:65], v[110:113], v[66:69], 0
	v_or_b32_e32 v0, 31, v190
	v_cmp_lt_i32_e32 vcc, s49, v0
	s_xor_b64 s[8:9], s[8:9], -1
	s_or_b64 s[8:9], s[8:9], vcc
	s_waitcnt vmcnt(6)
	v_mfma_f32_32x32x16_bf16 v[50:65], v[106:109], v[70:73], v[50:65]
	s_waitcnt vmcnt(5)
	v_mfma_f32_32x32x16_bf16 v[50:65], v[98:101], v[74:77], v[50:65]
	s_waitcnt vmcnt(4)
	v_mfma_f32_32x32x16_bf16 v[50:65], v[102:105], v[78:81], v[50:65]
	s_and_saveexec_b64 s[12:13], s[8:9]
	s_xor_b64 s[8:9], exec, s[12:13]
	s_cbranch_execz .LBB0_609
	v_add_u32_e32 v0, v190, v201
	v_cmp_ge_i32_e32 vcc, v134, v0
	s_nop 6
	v_fmamk_f32 v34, v50, 0x3e38aa3b, v138
	s_and_b64 vcc, s[6:7], vcc
	v_cndmask_b32_e32 v34, v237, v34, vcc
	v_cmp_gt_i32_e32 vcc, v134, v0
	v_fmamk_f32 v35, v51, 0x3e38aa3b, v139
	s_and_b64 vcc, s[6:7], vcc
	v_or_b32_e32 v36, 2, v0
	v_cndmask_b32_e32 v35, v237, v35, vcc
	v_cmp_ge_i32_e32 vcc, v134, v36
	v_fmamk_f32 v36, v52, 0x3e38aa3b, v140
	s_and_b64 vcc, s[6:7], vcc
	v_or_b32_e32 v37, 3, v0
	v_cndmask_b32_e32 v36, v237, v36, vcc
	v_cmp_ge_i32_e32 vcc, v134, v37
	v_fmamk_f32 v37, v53, 0x3e38aa3b, v141
	s_and_b64 vcc, s[6:7], vcc
	v_add_u32_e32 v38, 8, v0
	v_cndmask_b32_e32 v37, v237, v37, vcc
	v_cmp_ge_i32_e32 vcc, v134, v38
	v_fmamk_f32 v38, v54, 0x3e38aa3b, v142
	s_and_b64 vcc, s[6:7], vcc
	v_add_u32_e32 v39, 9, v0
	v_cndmask_b32_e32 v38, v237, v38, vcc
	v_cmp_ge_i32_e32 vcc, v134, v39
	v_fmamk_f32 v39, v55, 0x3e38aa3b, v143
	s_and_b64 vcc, s[6:7], vcc
	v_add_u32_e32 v40, 10, v0
	v_cndmask_b32_e32 v39, v237, v39, vcc
	v_cmp_ge_i32_e32 vcc, v134, v40
	v_fmamk_f32 v40, v56, 0x3e38aa3b, v144
	s_and_b64 vcc, s[6:7], vcc
	v_add_u32_e32 v41, 11, v0
	v_cndmask_b32_e32 v40, v237, v40, vcc
	v_cmp_ge_i32_e32 vcc, v134, v41
	v_fmamk_f32 v41, v57, 0x3e38aa3b, v145
	s_and_b64 vcc, s[6:7], vcc
	v_add_u32_e32 v42, 16, v0
	v_cndmask_b32_e32 v41, v237, v41, vcc
	v_cmp_ge_i32_e32 vcc, v134, v42
	v_fmamk_f32 v42, v58, 0x3e38aa3b, v146
	s_and_b64 vcc, s[6:7], vcc
	v_add_u32_e32 v43, 17, v0
	v_cndmask_b32_e32 v42, v237, v42, vcc
	v_cmp_ge_i32_e32 vcc, v134, v43
	v_fmamk_f32 v43, v59, 0x3e38aa3b, v147
	s_and_b64 vcc, s[6:7], vcc
	v_add_u32_e32 v44, 18, v0
	v_cndmask_b32_e32 v43, v237, v43, vcc
	v_cmp_ge_i32_e32 vcc, v134, v44
	v_fmamk_f32 v44, v60, 0x3e38aa3b, v148
	s_and_b64 vcc, s[6:7], vcc
	v_add_u32_e32 v45, 19, v0
	v_cndmask_b32_e32 v44, v237, v44, vcc
	v_cmp_ge_i32_e32 vcc, v134, v45
	v_fmamk_f32 v45, v61, 0x3e38aa3b, v149
	s_and_b64 vcc, s[6:7], vcc
	v_add_u32_e32 v46, 24, v0
	v_cndmask_b32_e32 v45, v237, v45, vcc
	v_cmp_ge_i32_e32 vcc, v134, v46
	v_fmamk_f32 v46, v62, 0x3e38aa3b, v150
	s_and_b64 vcc, s[6:7], vcc
	v_add_u32_e32 v47, 25, v0
	v_cndmask_b32_e32 v46, v237, v46, vcc
	v_cmp_ge_i32_e32 vcc, v134, v47
	v_fmamk_f32 v47, v63, 0x3e38aa3b, v151
	s_and_b64 vcc, s[6:7], vcc
	v_add_u32_e32 v48, 26, v0
	v_cndmask_b32_e32 v47, v237, v47, vcc
	v_cmp_ge_i32_e32 vcc, v134, v48
	v_fmamk_f32 v48, v64, 0x3e38aa3b, v152
	s_and_b64 vcc, s[6:7], vcc
	v_add_u32_e32 v0, 27, v0
	v_cndmask_b32_e32 v48, v237, v48, vcc
	v_cmp_ge_i32_e32 vcc, v134, v0
	v_fmamk_f32 v0, v65, 0x3e38aa3b, v153
	s_and_b64 vcc, s[6:7], vcc
	v_cndmask_b32_e32 v49, v237, v0, vcc

; #define BODY_S(KF, vA, KEY0) { f32x16 x = qk64(KF, qf); const bool fs_ = allmem && ((KEY0) + 31 <= t0); \
;             TOK_Y(x, KEY0, fs_, (member && dist >= 0)) \
;             osm_u(x, -slope2 * (float)(t0 - (KEY0)), m, l, o); pv64(vA, x, o); }
; DI void nsa_item8(const Ctx& c, int q8, int g, LAS unsigned char* lds, int wave, int lane_in, float kbound) {
;     ...
;         int cur, nb; PREVBLK(0x7fffffff, cur, nb)
;     ...
;         while (nb >= 0) {
;             const bool member = cur == nb; const bool allmem = !__any(!member);
;             const int key0 = nb * 64;
;             bf16x8 k0[4], k1[4]; bf16x8 w0[4], w1[4];
;             ldk64(k0, Ksp + (size_t)(key0 + 32) * PP); ldk64(k1, Ksp + (size_t)key0 * PP); ldv64(w0, Vsp + (size_t)(nb * 2 + 1) * 32768, 32); ldv64(w1, Vsp + (size_t)(nb * 2) * 32768, 32);
;             int ncur, nn; PREVBLK(nb, ncur, nn)
;             if (key0 + 32 <= t0 + 7) BODY_S(k0, w0, key0 + 32)
;             BODY_S(k1, w1, key0)
.LBB0_1063:
	v_lshlrev_b32_e32 v186, 6, v50
	v_mad_u64_u32 v[34:35], s[6:7], v186, s56, v[158:159]
	v_lshlrev_b32_e32 v0, 1, v50
	global_load_dwordx4 v[110:113], v[34:35], off
	global_load_dwordx4 v[106:109], v[34:35], off offset:32
	global_load_dwordx4 v[98:101], v[34:35], off offset:64
	global_load_dwordx4 v[102:105], v[34:35], off offset:96
	v_lshlrev_b64 v[34:35], 16, v[0:1]
	v_lshl_add_u64 v[34:35], v[160:161], 0, v[34:35]
	global_load_dwordx4 v[94:97], v[34:35], off
	global_load_dwordx4 v[90:93], v[34:35], off offset:16
	global_load_dwordx4 v[82:85], v[34:35], off offset:2048
	global_load_dwordx4 v[86:89], v[34:35], off offset:2064
	v_or_b32_e32 v223, 32, v186
	v_mad_u64_u32 v[228:229], s[6:7], v223, s56, v[158:159]
	global_load_dwordx4 v[34:37], v[228:229], off
	global_load_dwordx4 v[38:41], v[228:229], off offset:32
	global_load_dwordx4 v[240:243], v[228:229], off offset:64
	global_load_dwordx4 v[248:251], v[228:229], off offset:96
	v_cmp_eq_u32_e64 s[8:9], 0, v50
	v_cmp_eq_u32_e64 s[6:7], v180, v50
	v_cmp_ne_u32_e32 vcc, v180, v50
	v_cndmask_b32_e64 v224, 0, -1, s[8:9]
	v_max_i32_e32 v225, s25, v224
	v_cmp_lt_i32_e64 s[8:9], s25, v50
	s_cmp_eq_u64 vcc, 0
	v_or_b32_e32 v187, 32, v186
	v_cndmask_b32_e64 v224, v224, v225, s[8:9]
	v_max_i32_e32 v225, s34, v224
	v_cmp_lt_i32_e64 s[8:9], s34, v50
	v_cmp_ge_i32_e32 vcc, s47, v187
	s_nop 0
	v_cndmask_b32_e64 v224, v224, v225, s[8:9]
	v_max_i32_e32 v225, v171, v224
	v_cmp_lt_i32_e64 s[8:9], v171, v50
	s_nop 1
	v_cndmask_b32_e64 v224, v224, v225, s[8:9]
	v_max_i32_e32 v225, v190, v224
	v_cmp_lt_i32_e64 s[8:9], v190, v50
	s_nop 1
	v_cndmask_b32_e64 v224, v224, v225, s[8:9]
	v_max_i32_e32 v225, v192, v224
	v_cmp_lt_i32_e64 s[8:9], v192, v50
	s_nop 1
	v_cndmask_b32_e64 v224, v224, v225, s[8:9]
	v_max_i32_e32 v225, v193, v224
	v_cmp_lt_i32_e64 s[8:9], v193, v50
	s_nop 1
	v_cndmask_b32_e64 v224, v224, v225, s[8:9]
	v_max_i32_e32 v225, v191, v224
	v_cmp_lt_i32_e64 s[8:9], v191, v50
	s_nop 1
	v_cndmask_b32_e64 v180, v224, v225, s[8:9]
	ds_bpermute_b32 v224, v157, v180
	s_cselect_b64 s[8:9], -1, 0
	s_waitcnt lgkmcnt(0)
	v_max_i32_e32 v224, v224, v180
	ds_bpermute_b32 v225, v176, v224
	s_waitcnt lgkmcnt(0)
	v_max_i32_e32 v224, v225, v224
	ds_bpermute_b32 v225, v177, v224
	s_waitcnt lgkmcnt(0)
	v_max_i32_e32 v224, v225, v224
	ds_bpermute_b32 v225, v178, v224
	s_waitcnt lgkmcnt(0)
	v_max_i32_e32 v224, v225, v224
	ds_bpermute_b32 v225, v179, v224
	s_waitcnt lgkmcnt(0)
	v_max_i32_e32 v184, v225, v224
	ds_bpermute_b32 v185, v181, v184
	s_and_saveexec_b64 s[12:13], vcc
	s_cbranch_execz .Lnsa_skip2
	v_or_b32_e32 v0, 1, v0
	s_xor_b64 s[50:51], s[8:9], -1
	v_lshlrev_b64 v[42:43], 16, v[0:1]
	v_lshl_add_u64 v[42:43], v[160:161], 0, v[42:43]
	global_load_dwordx4 v[126:129], v[42:43], off
	global_load_dwordx4 v[122:125], v[42:43], off offset:16
	global_load_dwordx4 v[118:121], v[42:43], off offset:2048
	global_load_dwordx4 v[114:117], v[42:43], off offset:2064
	v_or_b32_e32 v0, 63, v186
	v_cmp_lt_u32_e32 vcc, s44, v0
	s_or_b64 s[50:51], s[50:51], vcc
	s_waitcnt vmcnt(7)
	v_mfma_f32_32x32x16_bf16 v[50:65], v[34:37], v[66:69], 0
	s_waitcnt vmcnt(6)
	v_mfma_f32_32x32x16_bf16 v[50:65], v[38:41], v[70:73], v[50:65]
	s_waitcnt vmcnt(5)
	v_mfma_f32_32x32x16_bf16 v[50:65], v[240:243], v[74:77], v[50:65]
	s_waitcnt vmcnt(4)
	v_mfma_f32_32x32x16_bf16 v[50:65], v[248:251], v[78:81], v[50:65]
	s_and_saveexec_b64 s[52:53], s[50:51]
	s_xor_b64 s[50:51], exec, s[52:53]
	s_cbranch_execz .LBB0_1066
	v_add_u32_e32 v0, v187, v201
	v_cmp_ge_i32_e32 vcc, v134, v0
	s_nop 6
	v_fmamk_f32 v34, v50, 0x3e38aa3b, v138
	s_and_b64 vcc, s[6:7], vcc
	v_cndmask_b32_e32 v34, v237, v34, vcc
	v_cmp_gt_i32_e32 vcc, v134, v0
	v_fmamk_f32 v35, v51, 0x3e38aa3b, v139
	s_and_b64 vcc, s[6:7], vcc
	v_or_b32_e32 v36, 2, v0
	v_cndmask_b32_e32 v35, v237, v35, vcc
	v_cmp_ge_i32_e32 vcc, v134, v36
	v_fmamk_f32 v36, v52, 0x3e38aa3b, v140
	s_and_b64 vcc, s[6:7], vcc
	v_or_b32_e32 v37, 3, v0
	v_cndmask_b32_e32 v36, v237, v36, vcc
	v_cmp_ge_i32_e32 vcc, v134, v37
	v_fmamk_f32 v37, v53, 0x3e38aa3b, v141
	s_and_b64 vcc, s[6:7], vcc
	v_add_u32_e32 v38, 8, v0
	v_cndmask_b32_e32 v37, v237, v37, vcc
	v_cmp_ge_i32_e32 vcc, v134, v38
	v_fmamk_f32 v38, v54, 0x3e38aa3b, v142
	s_and_b64 vcc, s[6:7], vcc
	v_add_u32_e32 v39, 9, v0
	v_cndmask_b32_e32 v38, v237, v38, vcc
	v_cmp_ge_i32_e32 vcc, v134, v39
	v_fmamk_f32 v39, v55, 0x3e38aa3b, v143
	s_and_b64 vcc, s[6:7], vcc
	v_add_u32_e32 v40, 10, v0
	v_cndmask_b32_e32 v39, v237, v39, vcc
	v_cmp_ge_i32_e32 vcc, v134, v40
	v_fmamk_f32 v40, v56, 0x3e38aa3b, v144
	s_and_b64 vcc, s[6:7], vcc
	v_add_u32_e32 v41, 11, v0
	v_cndmask_b32_e32 v40, v237, v40, vcc
	v_cmp_ge_i32_e32 vcc, v134, v41
	v_fmamk_f32 v41, v57, 0x3e38aa3b, v145
	s_and_b64 vcc, s[6:7], vcc
	v_add_u32_e32 v42, 16, v0
	v_cndmask_b32_e32 v41, v237, v41, vcc
	v_cmp_ge_i32_e32 vcc, v134, v42
	v_fmamk_f32 v42, v58, 0x3e38aa3b, v146
	s_and_b64 vcc, s[6:7], vcc
	v_add_u32_e32 v43, 17, v0
	v_cndmask_b32_e32 v42, v237, v42, vcc
	v_cmp_ge_i32_e32 vcc, v134, v43
	v_fmamk_f32 v43, v59, 0x3e38aa3b, v147
	s_and_b64 vcc, s[6:7], vcc
	v_add_u32_e32 v44, 18, v0
	v_cndmask_b32_e32 v43, v237, v43, vcc
	v_cmp_ge_i32_e32 vcc, v134, v44
	v_fmamk_f32 v44, v60, 0x3e38aa3b, v148
	s_and_b64 vcc, s[6:7], vcc
	v_add_u32_e32 v45, 19, v0
	v_cndmask_b32_e32 v44, v237, v44, vcc
	v_cmp_ge_i32_e32 vcc, v134, v45
	v_fmamk_f32 v45, v61, 0x3e38aa3b, v149
	s_and_b64 vcc, s[6:7], vcc
	v_add_u32_e32 v46, 24, v0
	v_cndmask_b32_e32 v45, v237, v45, vcc
	v_cmp_ge_i32_e32 vcc, v134, v46
	v_fmamk_f32 v46, v62, 0x3e38aa3b, v150
	s_and_b64 vcc, s[6:7], vcc
	v_add_u32_e32 v47, 25, v0
	v_cndmask_b32_e32 v46, v237, v46, vcc
	v_cmp_ge_i32_e32 vcc, v134, v47
	v_fmamk_f32 v47, v63, 0x3e38aa3b, v151
	s_and_b64 vcc, s[6:7], vcc
	v_add_u32_e32 v48, 26, v0
	v_cndmask_b32_e32 v47, v237, v47, vcc
	v_cmp_ge_i32_e32 vcc, v134, v48
	v_fmamk_f32 v48, v64, 0x3e38aa3b, v152
	s_and_b64 vcc, s[6:7], vcc
	v_add_u32_e32 v0, 27, v0
	v_cndmask_b32_e32 v48, v237, v48, vcc
	v_cmp_ge_i32_e32 vcc, v134, v0
	v_fmamk_f32 v0, v65, 0x3e38aa3b, v153
	s_and_b64 vcc, s[6:7], vcc
	v_cndmask_b32_e32 v49, v237, v0, vcc

; DI float ex2(float x) { return __builtin_amdgcn_exp2f(x); }
; DI void both_halves(float x, float& lo, float& hi) { auto rr = __builtin_amdgcn_permlane32_swap(__float_as_uint(x), __float_as_uint(x), false, false); lo = __uint_as_float(rr[0]); hi = __uint_as_float(rr[1]); }
; #define BODY_S(KF, vA, KEY0) { f32x16 x = qk64(KF, qf); const bool fs_ = allmem && ((KEY0) + 31 <= t0); \
;             TOK_Y(x, KEY0, fs_, (member && dist >= 0)) \
;             osm_u(x, -slope2 * (float)(t0 - (KEY0)), m, l, o); pv64(vA, x, o); }
; DI void osm_u(f32x16& x, float u, float& m, float& l, f32x16 (&o)[2]) {
;     float tm = x[0];
; #pragma unroll
;     for (int i = 1; i < 16; ++i) tm = fmaxf(tm, x[i]);
;     float lo, hi; both_halves(tm, lo, hi); tm = fmaxf(lo, hi);
;     const float mn = fmaxf(m, tm + u);
;     if (__any(mn != m)) { const float alpha = ex2(m - mn); l *= alpha; o[0] = o[0] * alpha; o[1] = o[1] * alpha; m = mn; }
;     const float sh = u - m; float ps = 0.f;
; #pragma unroll
;     for (int i = 0; i < 16; ++i) { x[i] = ex2(x[i] + sh); ps += x[i]; }
;     l += ps;
; }
; DI void nsa_item8(const Ctx& c, int q8, int g, LAS unsigned char* lds, int wave, int lane_in, float kbound) {
;     ...
;             BODY_S(k1, w1, key0)
.LBB0_1072:
	v_mul_f32_e64 v0, -v132, v0
	v_sub_f32_e32 v0, v0, v50
	v_add_f32_e32 v34, v34, v0
	v_exp_f32_e32 v34, v34
	v_add_f32_e32 v35, v35, v0
	v_exp_f32_e32 v35, v35
	v_add_f32_e32 v36, v36, v0
	v_exp_f32_e32 v36, v36
	v_add_f32_e32 v37, v37, v0
	v_add_f32_e32 v38, v38, v0
	v_add_f32_e32 v39, v39, v0
	v_add_f32_e32 v40, v40, v0
	v_add_f32_e32 v41, v41, v0
	v_exp_f32_e32 v37, v37
	v_exp_f32_e32 v38, v38
	v_exp_f32_e32 v39, v39
	v_exp_f32_e32 v40, v40
	v_exp_f32_e32 v41, v41
	v_add_f32_e32 v50, 0, v34
	v_add_f32_e32 v50, v35, v50
	v_add_f32_e32 v50, v36, v50
	v_add_f32_e32 v50, v37, v50
	v_cvt_pk_bf16_f32 v34, v34, v35
	v_cvt_pk_bf16_f32 v35, v36, v37
	v_cvt_pk_bf16_f32 v36, v38, v39
	v_cvt_pk_bf16_f32 v37, v40, v41
	v_add_f32_e32 v42, v42, v0
	v_add_f32_e32 v43, v43, v0
	s_waitcnt vmcnt(3)
	v_mfma_f32_32x32x16_bf16 v[18:33], v[126:129], v[34:37], v[18:33]
	v_add_f32_e32 v44, v44, v0
	v_add_f32_e32 v45, v45, v0
	v_add_f32_e32 v46, v46, v0
	v_add_f32_e32 v47, v47, v0
	v_add_f32_e32 v48, v48, v0
	v_add_f32_e32 v0, v49, v0
	v_add_f32_e32 v50, v38, v50
	s_waitcnt vmcnt(1)
	v_mfma_f32_32x32x16_bf16 v[2:17], v[118:121], v[34:37], v[2:17]
	v_exp_f32_e32 v42, v42
	v_exp_f32_e32 v43, v43
	v_exp_f32_e32 v44, v44
	v_exp_f32_e32 v45, v45
	v_exp_f32_e32 v46, v46
	v_exp_f32_e32 v47, v47
	v_exp_f32_e32 v48, v48
	v_exp_f32_e32 v0, v0
	v_add_f32_e32 v50, v39, v50
	v_add_f32_e32 v50, v40, v50
	v_add_f32_e32 v50, v41, v50
	v_add_f32_e32 v50, v42, v50
	v_cvt_pk_bf16_f32 v38, v42, v43
	v_cvt_pk_bf16_f32 v39, v44, v45
	v_cvt_pk_bf16_f32 v40, v46, v47
	v_cvt_pk_bf16_f32 v41, v48, v0
	v_add_f32_e32 v50, v43, v50
	v_add_f32_e32 v50, v44, v50
	v_mfma_f32_32x32x16_bf16 v[18:33], v[122:125], v[38:41], v[18:33]
	v_add_f32_e32 v50, v45, v50
	v_add_f32_e32 v50, v46, v50
	v_add_f32_e32 v50, v47, v50
	v_add_f32_e32 v50, v48, v50
	v_add_f32_e32 v49, v0, v50
	v_add_f32_e32 v182, v182, v49
	s_waitcnt vmcnt(0)
	v_mfma_f32_32x32x16_bf16 v[2:17], v[114:117], v[38:41], v[2:17]
.Lnsa_skip2:
	s_waitcnt vmcnt(0)
.LBB0_1073:
	s_or_b64 exec, exec, s[12:13]
	s_waitcnt vmcnt(7)
	v_mfma_f32_32x32x16_bf16 v[50:65], v[110:113], v[66:69], 0
	v_or_b32_e32 v0, 31, v186
	v_cmp_lt_i32_e32 vcc, s44, v0
	s_xor_b64 s[8:9], s[8:9], -1
	s_or_b64 s[8:9], s[8:9], vcc
	s_waitcnt vmcnt(6)
	v_mfma_f32_32x32x16_bf16 v[50:65], v[106:109], v[70:73], v[50:65]
	s_waitcnt vmcnt(5)
	v_mfma_f32_32x32x16_bf16 v[50:65], v[98:101], v[74:77], v[50:65]
	s_waitcnt vmcnt(4)
	v_mfma_f32_32x32x16_bf16 v[50:65], v[102:105], v[78:81], v[50:65]
	s_and_saveexec_b64 s[12:13], s[8:9]
	s_xor_b64 s[8:9], exec, s[12:13]
	s_cbranch_execz .LBB0_1075
	v_add_u32_e32 v0, v186, v201
	v_cmp_ge_i32_e32 vcc, v134, v0
	s_nop 6
	v_fmamk_f32 v34, v50, 0x3e38aa3b, v138
	s_and_b64 vcc, s[6:7], vcc
	v_cndmask_b32_e32 v34, v237, v34, vcc
	v_cmp_gt_i32_e32 vcc, v134, v0
	v_fmamk_f32 v35, v51, 0x3e38aa3b, v139
	s_and_b64 vcc, s[6:7], vcc
	v_or_b32_e32 v36, 2, v0
	v_cndmask_b32_e32 v35, v237, v35, vcc
	v_cmp_ge_i32_e32 vcc, v134, v36
	v_fmamk_f32 v36, v52, 0x3e38aa3b, v140
	s_and_b64 vcc, s[6:7], vcc
	v_or_b32_e32 v37, 3, v0
	v_cndmask_b32_e32 v36, v237, v36, vcc
	v_cmp_ge_i32_e32 vcc, v134, v37
	v_fmamk_f32 v37, v53, 0x3e38aa3b, v141
	s_and_b64 vcc, s[6:7], vcc
	v_add_u32_e32 v38, 8, v0
	v_cndmask_b32_e32 v37, v237, v37, vcc
	v_cmp_ge_i32_e32 vcc, v134, v38
	v_fmamk_f32 v38, v54, 0x3e38aa3b, v142
	s_and_b64 vcc, s[6:7], vcc
	v_add_u32_e32 v39, 9, v0
	v_cndmask_b32_e32 v38, v237, v38, vcc
	v_cmp_ge_i32_e32 vcc, v134, v39
	v_fmamk_f32 v39, v55, 0x3e38aa3b, v143
	s_and_b64 vcc, s[6:7], vcc
	v_add_u32_e32 v40, 10, v0
	v_cndmask_b32_e32 v39, v237, v39, vcc
	v_cmp_ge_i32_e32 vcc, v134, v40
	v_fmamk_f32 v40, v56, 0x3e38aa3b, v144
	s_and_b64 vcc, s[6:7], vcc
	v_add_u32_e32 v41, 11, v0
	v_cndmask_b32_e32 v40, v237, v40, vcc
	v_cmp_ge_i32_e32 vcc, v134, v41
	v_fmamk_f32 v41, v57, 0x3e38aa3b, v145
	s_and_b64 vcc, s[6:7], vcc
	v_add_u32_e32 v42, 16, v0
	v_cndmask_b32_e32 v41, v237, v41, vcc
	v_cmp_ge_i32_e32 vcc, v134, v42
	v_fmamk_f32 v42, v58, 0x3e38aa3b, v146
	s_and_b64 vcc, s[6:7], vcc
	v_add_u32_e32 v43, 17, v0
	v_cndmask_b32_e32 v42, v237, v42, vcc
	v_cmp_ge_i32_e32 vcc, v134, v43
	v_fmamk_f32 v43, v59, 0x3e38aa3b, v147
	s_and_b64 vcc, s[6:7], vcc
	v_add_u32_e32 v44, 18, v0
	v_cndmask_b32_e32 v43, v237, v43, vcc
	v_cmp_ge_i32_e32 vcc, v134, v44
	v_fmamk_f32 v44, v60, 0x3e38aa3b, v148
	s_and_b64 vcc, s[6:7], vcc
	v_add_u32_e32 v45, 19, v0
	v_cndmask_b32_e32 v44, v237, v44, vcc
	v_cmp_ge_i32_e32 vcc, v134, v45
	v_fmamk_f32 v45, v61, 0x3e38aa3b, v149
	s_and_b64 vcc, s[6:7], vcc
	v_add_u32_e32 v46, 24, v0
	v_cndmask_b32_e32 v45, v237, v45, vcc
	v_cmp_ge_i32_e32 vcc, v134, v46
	v_fmamk_f32 v46, v62, 0x3e38aa3b, v150
	s_and_b64 vcc, s[6:7], vcc
	v_add_u32_e32 v47, 25, v0
	v_cndmask_b32_e32 v46, v237, v46, vcc
	v_cmp_ge_i32_e32 vcc, v134, v47
	v_fmamk_f32 v47, v63, 0x3e38aa3b, v151
	s_and_b64 vcc, s[6:7], vcc
	v_add_u32_e32 v48, 26, v0
	v_cndmask_b32_e32 v47, v237, v47, vcc
	v_cmp_ge_i32_e32 vcc, v134, v48
	v_fmamk_f32 v48, v64, 0x3e38aa3b, v152
	s_and_b64 vcc, s[6:7], vcc
	v_add_u32_e32 v0, 27, v0
	v_cndmask_b32_e32 v48, v237, v48, vcc
	v_cmp_ge_i32_e32 vcc, v134, v0
	v_fmamk_f32 v0, v65, 0x3e38aa3b, v153
	s_and_b64 vcc, s[6:7], vcc
	v_cndmask_b32_e32 v49, v237, v0, vcc

; __global__ void __launch_bounds__(512) fwd(Args a_) {
	.amdhsa_kernel _Z3fwd4Args
		.amdhsa_group_segment_fixed_size 8704
		.amdhsa_private_segment_fixed_size 0
		.amdhsa_kernarg_size 432
		.amdhsa_user_sgpr_count 2
		.amdhsa_user_sgpr_dispatch_ptr 0
		.amdhsa_user_sgpr_queue_ptr 0
		.amdhsa_user_sgpr_kernarg_segment_ptr 1
		.amdhsa_user_sgpr_dispatch_id 0
		.amdhsa_user_sgpr_kernarg_preload_length 0
		.amdhsa_user_sgpr_kernarg_preload_offset 0
		.amdhsa_user_sgpr_private_segment_size 0
		.amdhsa_uses_dynamic_stack 0
		.amdhsa_enable_private_segment 0
		.amdhsa_system_sgpr_workgroup_id_x 1
		.amdhsa_system_sgpr_workgroup_id_y 0
		.amdhsa_system_sgpr_workgroup_id_z 0
		.amdhsa_system_sgpr_workgroup_info 0
		.amdhsa_system_vgpr_workitem_id 2
		.amdhsa_next_free_vgpr 256
		.amdhsa_next_free_sgpr 102
		.amdhsa_accum_offset 256
		.amdhsa_reserve_vcc 1
		.amdhsa_float_round_mode_32 0
		.amdhsa_float_round_mode_16_64 0
		.amdhsa_float_denorm_mode_32 3
		.amdhsa_float_denorm_mode_16_64 3
		.amdhsa_dx10_clamp 1
		.amdhsa_ieee_mode 1
		.amdhsa_fp16_overflow 0
		.amdhsa_tg_split 0
		.amdhsa_exception_fp_ieee_invalid_op 0
		.amdhsa_exception_fp_denorm_src 0
		.amdhsa_exception_fp_ieee_div_zero 0
		.amdhsa_exception_fp_ieee_overflow 0
		.amdhsa_exception_fp_ieee_underflow 0
		.amdhsa_exception_fp_ieee_inexact 0
		.amdhsa_exception_int_div_zero 0
	.end_amdhsa_kernel

; __global__ void __launch_bounds__(512) fwd(Args a_) {
amdhsa.kernels:
  - .agpr_count:     0
    .args:
      - .offset:         0
        .size:           176
        .value_kind:     by_value
      - .offset:         176
        .size:           4
        .value_kind:     hidden_block_count_x
      - .offset:         180
        .size:           4
        .value_kind:     hidden_block_count_y
      - .offset:         184
        .size:           4
        .value_kind:     hidden_block_count_z
      - .offset:         188
        .size:           2
        .value_kind:     hidden_group_size_x
      - .offset:         190
        .size:           2
        .value_kind:     hidden_group_size_y
      - .offset:         192
        .size:           2
        .value_kind:     hidden_group_size_z
      - .offset:         194
        .size:           2
        .value_kind:     hidden_remainder_x
      - .offset:         196
        .size:           2
        .value_kind:     hidden_remainder_y
      - .offset:         198
        .size:           2
        .value_kind:     hidden_remainder_z
      - .offset:         216
        .size:           8
        .value_kind:     hidden_global_offset_x
      - .offset:         224
        .size:           8
        .value_kind:     hidden_global_offset_y
      - .offset:         232
        .size:           8
        .value_kind:     hidden_global_offset_z
      - .offset:         240
        .size:           2
        .value_kind:     hidden_grid_dims
      - .offset:         264
        .size:           8
        .value_kind:     hidden_multigrid_sync_arg
      - .offset:         296
        .size:           4
        .value_kind:     hidden_dynamic_lds_size
    .group_segment_fixed_size: 8704
    .kernarg_segment_align: 8
    .kernarg_segment_size: 432
    .language:       OpenCL C
    .language_version:
      - 2
      - 0
    .max_flat_workgroup_size: 512
    .name:           _Z3fwd4Args
    .private_segment_fixed_size: 0
    .sgpr_count:     108
    .sgpr_spill_count: 49
    .symbol:         _Z3fwd4Args.kd
    .uniform_work_group_size: 1
    .uses_dynamic_stack: false
    .vgpr_count:     256
    .vgpr_spill_count: 0
    .wavefront_size: 64
